# odd projection: fp32 neighbourhood-cache K/V outputs written in one full-line pass over the LDS image
# speedup vs baseline: 1.0061x; 1.0025x over previous
.LBB0_1277:
	v_lshl_or_b32 v138, v172, 2, s22
	v_mad_u64_u32 v[150:151], s[6:7], v131, s29, v[138:139]
	v_cvt_pk_bf16_f32 v98, v98, v99
	v_cvt_pk_bf16_f32 v99, v100, v101
	v_cvt_pk_bf16_f32 v66, v66, v67
	v_cvt_pk_bf16_f32 v58, v58, v59
	v_cvt_pk_bf16_f32 v59, v60, v61
	s_nop 0
	v_lshl_add_u32 v131, v150, 1, 0
	v_add_u32_e32 v100, 0x6000, v131
	v_add_u32_e32 v60, 0x10820, v131
	v_cvt_pk_bf16_f32 v50, v50, v51
	v_cvt_pk_bf16_f32 v51, v52, v53
	v_add_u32_e32 v52, 0x12920, v131
	v_cvt_pk_bf16_f32 v42, v42, v43
	v_cvt_pk_bf16_f32 v43, v44, v45
	v_add_u32_e32 v44, 0x14a20, v131
	v_cvt_pk_bf16_f32 v34, v34, v35
	v_cvt_pk_bf16_f32 v35, v36, v37
	v_add_u32_e32 v36, 0x16b20, v131
	v_cvt_pk_bf16_f32 v26, v26, v27
	v_cvt_pk_bf16_f32 v27, v28, v29
	v_add_u32_e32 v28, 0x10920, v131
	v_cvt_pk_bf16_f32 v18, v18, v19
	v_cvt_pk_bf16_f32 v19, v20, v21
	v_add_u32_e32 v20, 0x12a20, v131
	v_cvt_pk_bf16_f32 v10, v10, v11
	v_cvt_pk_bf16_f32 v11, v12, v13
	v_add_u32_e32 v12, 0x14b20, v131
	s_lshl_b32 s36, s23, 4
	v_cvt_pk_bf16_f32 v114, v114, v115
	v_cvt_pk_bf16_f32 v115, v116, v117
	v_add_u32_e32 v116, 0x2000, v131
	v_cvt_pk_bf16_f32 v106, v106, v107
	v_cvt_pk_bf16_f32 v107, v108, v109
	v_add_u32_e32 v108, 0x4000, v131
	v_cvt_pk_bf16_f32 v70, v70, v71
	v_cvt_pk_bf16_f32 v71, v72, v73
	v_cvt_pk_bf16_f32 v67, v68, v69
	ds_write2_b64 v100, v[70:71], v[66:67] offset0:128 offset1:132
	v_add_u32_e32 v66, 0x10800, v131
	ds_write_b64 v60, v[58:59]
	v_add_u32_e32 v58, 0x12900, v131
	ds_write_b64 v52, v[50:51]
	v_add_u32_e32 v50, 0x14a00, v131
	ds_write_b64 v44, v[42:43]
	v_add_u32_e32 v42, 0x16b00, v131
	ds_write_b64 v36, v[34:35]
	v_add_u32_e32 v34, 0x10900, v131
	ds_write_b64 v28, v[26:27]
	v_add_u32_e32 v26, 0x12a00, v131
	ds_write_b64 v20, v[18:19]
	v_add_u32_e32 v18, 0x14b00, v131
	ds_write_b64 v12, v[10:11]
	v_add_u32_e32 v10, 0x16c00, v131
	v_cvt_pk_bf16_f32 v2, v2, v3
	v_cvt_pk_bf16_f32 v3, v4, v5
	v_add_u32_e32 v4, 0x16c20, v131
	s_lshl_b32 s22, s23, 1
	s_lshl_b32 s35, s21, 1
	s_add_i32 s37, s36, -16
	v_cvt_pk_bf16_f32 v126, v126, v127
	v_cvt_pk_bf16_f32 v127, v128, v129
	v_cvt_pk_bf16_f32 v122, v122, v123
	v_cvt_pk_bf16_f32 v123, v124, v125
	ds_write2_b64 v131, v[126:127], v[122:123] offset1:4
	v_cvt_pk_bf16_f32 v118, v118, v119
	v_cvt_pk_bf16_f32 v119, v120, v121
	ds_write2_b64 v116, v[118:119], v[114:115] offset0:32 offset1:36
	v_cvt_pk_bf16_f32 v110, v110, v111
	v_cvt_pk_bf16_f32 v111, v112, v113
	ds_write2_b64 v108, v[110:111], v[106:107] offset0:64 offset1:68
	v_cvt_pk_bf16_f32 v102, v102, v103
	v_cvt_pk_bf16_f32 v103, v104, v105
	ds_write2_b64 v100, v[102:103], v[98:99] offset0:96 offset1:100
	v_cvt_pk_bf16_f32 v94, v94, v95
	v_cvt_pk_bf16_f32 v95, v96, v97
	v_cvt_pk_bf16_f32 v90, v90, v91
	v_cvt_pk_bf16_f32 v91, v92, v93
	ds_write2_b64 v131, v[94:95], v[90:91] offset0:32 offset1:36
	v_cvt_pk_bf16_f32 v86, v86, v87
	v_cvt_pk_bf16_f32 v87, v88, v89
	v_cvt_pk_bf16_f32 v82, v82, v83
	v_cvt_pk_bf16_f32 v83, v84, v85
	ds_write2_b64 v116, v[86:87], v[82:83] offset0:64 offset1:68
	v_cvt_pk_bf16_f32 v78, v78, v79
	v_cvt_pk_bf16_f32 v79, v80, v81
	v_cvt_pk_bf16_f32 v74, v74, v75
	v_cvt_pk_bf16_f32 v75, v76, v77
	ds_write2_b64 v108, v[78:79], v[74:75] offset0:96 offset1:100
	v_cvt_pk_bf16_f32 v62, v62, v63
	v_cvt_pk_bf16_f32 v63, v64, v65
	ds_write_b64 v66, v[62:63]
	v_cvt_pk_bf16_f32 v54, v54, v55
	v_cvt_pk_bf16_f32 v55, v56, v57
	ds_write_b64 v58, v[54:55]
	v_cvt_pk_bf16_f32 v46, v46, v47
	v_cvt_pk_bf16_f32 v47, v48, v49
	ds_write_b64 v50, v[46:47]
	v_cvt_pk_bf16_f32 v38, v38, v39
	v_cvt_pk_bf16_f32 v39, v40, v41
	ds_write_b64 v42, v[38:39]
	v_cvt_pk_bf16_f32 v30, v30, v31
	v_cvt_pk_bf16_f32 v31, v32, v33
	ds_write_b64 v34, v[30:31]
	v_cvt_pk_bf16_f32 v22, v22, v23
	v_cvt_pk_bf16_f32 v23, v24, v25
	ds_write_b64 v26, v[22:23]
	v_cvt_pk_bf16_f32 v14, v14, v15
	v_cvt_pk_bf16_f32 v15, v16, v17
	ds_write_b64 v18, v[14:15]
	v_cvt_pk_bf16_f32 v6, v6, v7
	v_cvt_pk_bf16_f32 v7, v8, v9
	ds_write_b64 v10, v[6:7]
	ds_write_b64 v4, v[2:3]
	s_waitcnt lgkmcnt(0)
	s_barrier
	s_cmp_gt_i32 s22, 63
	s_cbranch_scc1 .Lnkv_skip
	s_lshr_b32 s6, s35, 1
	s_cmp_lt_i32 s6, 4
	s_cbranch_scc1 .Lnkv_skip
	s_lshr_b32 s7, s22, 1
	s_mov_b32 s8, 0x7800000
	s_cmp_lt_i32 s6, 8
	s_cselect_b32 s8, 0x5800000, s8
	s_cselect_b32 s24, 4, 8
	s_sub_i32 s6, s6, s24
	s_lshl_b32 s6, s6, 2
	s_lshl_b32 s7, s7, 4
	s_add_i32 s6, s6, s7
	s_lshl_b32 s6, s6, 16
	s_add_u32 s8, s8, s6
	v_readlane_b32 s46, v254, 0
	v_readlane_b32 s47, v254, 1
	s_load_dwordx2 s[44:45], s[46:47], 0xe8
	v_lshrrev_b32_e32 v100, 4, v0
	v_and_b32_e32 v100, 3, v100
	v_lshlrev_b32_e32 v100, 16, v100
	v_lshrrev_b32_e32 v101, 6, v0
	v_lshl_or_b32 v100, v101, 8, v100
	v_and_b32_e32 v102, 15, v0
	v_lshl_or_b32 v100, v102, 4, v100
	v_add_u32_e32 v129, 0x1000, v100
	v_mul_u32_u24_e32 v103, 0x210, v101
	v_and_b32_e32 v102, 63, v0
	v_lshl_add_u32 v103, v102, 3, v103
	s_waitcnt lgkmcnt(0)
	s_add_u32 s44, s44, s8
	s_addc_u32 s45, s45, 0
	s_mov_b32 s24, 8
.Lnkv_loop:
	ds_read_b64 v[104:105], v103
	ds_read_b64 v[106:107], v103 offset:4224
	ds_read_b64 v[108:109], v103 offset:8448
	ds_read_b64 v[110:111], v103 offset:12672
	s_waitcnt lgkmcnt(3)
	v_lshlrev_b32_e32 v112, 16, v104
	v_and_b32_e32 v113, 0xffff0000, v104
	v_lshlrev_b32_e32 v114, 16, v105
	v_and_b32_e32 v115, 0xffff0000, v105
	global_store_dwordx4 v100, v[112:115], s[44:45]
	s_waitcnt lgkmcnt(2)
	v_lshlrev_b32_e32 v116, 16, v106
	v_and_b32_e32 v117, 0xffff0000, v106
	v_lshlrev_b32_e32 v118, 16, v107
	v_and_b32_e32 v119, 0xffff0000, v107
	global_store_dwordx4 v100, v[116:119], s[44:45] offset:2048
	s_waitcnt lgkmcnt(1)
	v_lshlrev_b32_e32 v120, 16, v108
	v_and_b32_e32 v121, 0xffff0000, v108
	v_lshlrev_b32_e32 v122, 16, v109
	v_and_b32_e32 v123, 0xffff0000, v109
	global_store_dwordx4 v129, v[120:123], s[44:45]
	s_waitcnt lgkmcnt(0)
	v_lshlrev_b32_e32 v124, 16, v110
	v_and_b32_e32 v125, 0xffff0000, v110
	v_lshlrev_b32_e32 v126, 16, v111
	v_and_b32_e32 v127, 0xffff0000, v111
	global_store_dwordx4 v129, v[124:127], s[44:45] offset:2048
	v_add_u32_e32 v100, 0x2000, v100
	v_add_u32_e32 v129, 0x2000, v129
	v_add_u32_e32 v103, 0x4200, v103
	s_sub_i32 s24, s24, 1
	s_cmp_lg_u32 s24, 0
	s_cbranch_scc1 .Lnkv_loop
.Lnkv_skip:
	s_branch .LBB0_1279
.LBB0_1278:
	s_add_i32 s20, s20, 1
	s_cmp_lg_u32 s20, 4
	s_cbranch_scc0 .LBB0_1260
.LBB0_1279:
	s_lshr_b32 s6, s20, 1
	s_and_b32 s7, s20, 1
	s_add_i32 s8, s6, s22
	s_mul_i32 s6, s6, 0x10800
	s_add_i32 s39, s6, 0
	s_lshl_b32 s6, s7, 8
	s_or_b32 s40, s7, s35
	s_add_i32 s39, s39, s6
	s_lshl_b32 s26, s8, 7
	s_cmp_gt_i32 s8, 63
	s_cselect_b64 s[6:7], -1, 0
	s_cmp_lt_i32 s8, 64
	s_cselect_b64 s[24:25], -1, 0
	s_add_i32 s8, s26, 0xffffe000
	v_mov_b32_e32 v7, v0
	s_lshr_b32 s42, s8, 10
	s_and_b32 s41, s26, 0x380
	s_and_b32 s38, s26, 0x80
	s_cmp_gt_i32 s40, 15
	v_and_b32_e32 v6, 15, v7
	v_ashrrev_i32_e32 v2, 4, v7
	s_mov_b64 s[26:27], -1
	s_cbranch_scc0 .LBB0_1283
	v_mov_b32_e32 v3, v0
	s_and_b64 s[26:27], s[6:7], exec
	s_cselect_b32 s26, s42, s23
	v_ashrrev_i32_e32 v8, 7, v3
	v_bfe_u32 v5, v3, 2, 7
	v_bfi_b32 v14, -4, v8, v3
	s_cselect_b32 s8, s41, s38
	s_lshl_b32 s27, s40, 1
	s_lshl_b32 s26, s26, 4
	v_mul_lo_u32 v8, v14, s30
	v_lshlrev_b32_e32 v15, 1, v5
	s_add_i32 s43, s27, s26
	v_add3_u32 v5, s39, v8, v15
	s_and_b64 s[26:27], s[6:7], exec
	ds_read_u16 v8, v5
	ds_read_u16 v9, v5 offset:528
	ds_read_u16 v10, v5 offset:1056
	ds_read_u16 v11, v5 offset:1584
	ds_read_u16 v12, v5 offset:2112
	ds_read_u16 v13, v5 offset:2640
	ds_read_u16 v16, v5 offset:3168
	ds_read_u16 v5, v5 offset:3696
	s_cselect_b32 s26, 0x1000000, 0
	s_add_u32 s44, s2, s26
	v_lshrrev_b32_e32 v4, 2, v3
	s_addc_u32 s45, s3, 0
	v_bfe_u32 v4, v4, 6, 1
	s_sub_i32 s26, s43, 32
	v_or_b32_e32 v4, s26, v4
	s_and_b64 s[46:47], s[6:7], exec
	s_waitcnt lgkmcnt(6)
	v_lshl_or_b32 v8, v9, 16, v8
	s_waitcnt lgkmcnt(4)
	v_lshl_or_b32 v9, v11, 16, v10
	s_waitcnt lgkmcnt(0)
	v_lshl_or_b32 v11, v5, 16, v16
	v_ashrrev_i32_e32 v5, 31, v4
	s_cselect_b32 s27, 4, 2
	v_lshlrev_b64 v[4:5], s27, v[4:5]
	s_lshr_b32 s8, s8, 6
	v_lshl_add_u64 v[4:5], v[4:5], 0, s[8:9]
	v_lshl_or_b32 v10, v13, 16, v12
	v_lshlrev_b64 v[4:5], 13, v[4:5]
	v_lshlrev_b32_e32 v12, 5, v3
	v_lshl_add_u64 v[4:5], s[44:45], 0, v[4:5]
	v_and_b32_e32 v138, 0x1f80, v12
	v_lshlrev_b32_e32 v14, 4, v14
	v_lshl_add_u64 v[4:5], v[4:5], 0, v[138:139]
	v_and_b32_e32 v138, 0x70, v14
	v_add_u32_e32 v14, 0x200, v3
	v_ashrrev_i32_e32 v12, 10, v3
	v_ashrrev_i32_e32 v16, 7, v14
	v_ashrrev_i32_e32 v13, 31, v12
	v_bfi_b32 v16, -4, v16, v3
	v_lshlrev_b64 v[12:13], 13, v[12:13]
	v_mul_lo_u32 v17, v16, s30
	v_lshl_add_u64 v[12:13], v[4:5], 0, v[12:13]
	v_add3_u32 v17, s39, v17, v15
	v_lshl_add_u64 v[12:13], v[12:13], 0, v[138:139]
	ds_read_u16 v18, v17
	ds_read_u16 v19, v17 offset:528
	ds_read_u16 v20, v17 offset:1056
	ds_read_u16 v21, v17 offset:1584
	ds_read_u16 v22, v17 offset:2112
	ds_read_u16 v23, v17 offset:2640
	ds_read_u16 v24, v17 offset:3168
	ds_read_u16 v17, v17 offset:3696
	global_store_dwordx4 v[12:13], v[8:11], off
	v_ashrrev_i32_e32 v12, 10, v14
	v_lshlrev_b32_e32 v14, 4, v16
	v_and_b32_e32 v138, 0x70, v14
	v_add_u32_e32 v14, 0x400, v3
	v_ashrrev_i32_e32 v13, 31, v12
	v_ashrrev_i32_e32 v16, 7, v14
	v_lshlrev_b64 v[12:13], 13, v[12:13]
	v_bfi_b32 v16, -4, v16, v3
	s_waitcnt lgkmcnt(0)
	v_lshl_or_b32 v11, v17, 16, v24
	v_lshl_add_u64 v[12:13], v[4:5], 0, v[12:13]
	v_mul_lo_u32 v17, v16, s30
	v_lshl_or_b32 v8, v19, 16, v18
	v_lshl_or_b32 v9, v21, 16, v20
	v_lshl_or_b32 v10, v23, 16, v22
	v_lshl_add_u64 v[12:13], v[12:13], 0, v[138:139]
	v_add3_u32 v17, s39, v17, v15
	ds_read_u16 v18, v17
	ds_read_u16 v19, v17 offset:528
	ds_read_u16 v20, v17 offset:1056
	ds_read_u16 v21, v17 offset:1584
	ds_read_u16 v22, v17 offset:2112
	ds_read_u16 v23, v17 offset:2640
	ds_read_u16 v24, v17 offset:3168
	ds_read_u16 v17, v17 offset:3696
	global_store_dwordx4 v[12:13], v[8:11], off
	v_ashrrev_i32_e32 v12, 10, v14
	v_lshlrev_b32_e32 v14, 4, v16
	v_and_b32_e32 v138, 0x70, v14
	v_add_u32_e32 v14, 0x600, v3
	v_ashrrev_i32_e32 v16, 7, v14
	v_ashrrev_i32_e32 v13, 31, v12
	v_bfi_b32 v3, -4, v16, v3
	v_lshlrev_b64 v[12:13], 13, v[12:13]
	v_mul_lo_u32 v16, v3, s30
	v_lshl_add_u64 v[12:13], v[4:5], 0, v[12:13]
	v_add3_u32 v15, s39, v16, v15
	s_waitcnt lgkmcnt(6)
	v_lshl_or_b32 v8, v19, 16, v18
	s_waitcnt lgkmcnt(4)
	v_lshl_or_b32 v9, v21, 16, v20
	s_waitcnt lgkmcnt(2)
	v_lshl_or_b32 v10, v23, 16, v22
	s_waitcnt lgkmcnt(0)
	v_lshl_or_b32 v11, v17, 16, v24
	v_lshl_add_u64 v[12:13], v[12:13], 0, v[138:139]
	ds_read_u16 v16, v15
	ds_read_u16 v17, v15 offset:528
	ds_read_u16 v18, v15 offset:1056
	ds_read_u16 v19, v15 offset:1584
	ds_read_u16 v20, v15 offset:2112
	ds_read_u16 v21, v15 offset:2640
	ds_read_u16 v22, v15 offset:3168
	ds_read_u16 v15, v15 offset:3696
	global_store_dwordx4 v[12:13], v[8:11], off
	v_ashrrev_i32_e32 v12, 10, v14
	v_ashrrev_i32_e32 v13, 31, v12
	v_lshlrev_b64 v[12:13], 13, v[12:13]
	v_lshlrev_b32_e32 v3, 4, v3
	v_lshl_add_u64 v[4:5], v[4:5], 0, v[12:13]
	v_and_b32_e32 v138, 0x70, v3
	s_waitcnt lgkmcnt(6)
	v_lshl_or_b32 v8, v17, 16, v16
	s_waitcnt lgkmcnt(4)
	v_lshl_or_b32 v9, v19, 16, v18
	s_waitcnt lgkmcnt(2)
	v_lshl_or_b32 v10, v21, 16, v20
	s_waitcnt lgkmcnt(0)
	v_lshl_or_b32 v11, v15, 16, v22
	v_lshl_add_u64 v[4:5], v[4:5], 0, v[138:139]
	s_andn2_b64 vcc, exec, s[24:25]
	global_store_dwordx4 v[4:5], v[8:11], off
	s_cbranch_vccnz .LBB0_1282
	v_lshrrev_b32_e32 v4, 3, v6
	v_or_b32_e32 v4, s26, v4
	v_ashrrev_i32_e32 v5, 31, v4
	v_lshlrev_b32_e32 v3, 4, v6
	v_lshlrev_b64 v[4:5], 8, v[4:5]
	v_mul_lo_u32 v8, v2, s31
	v_or_b32_e32 v4, s38, v4
	v_add3_u32 v26, s39, v3, v8
	v_ashrrev_i32_e32 v3, 31, v2
	v_lshl_add_u64 v[8:9], v[4:5], 0, v[2:3]
	v_lshlrev_b64 v[8:9], 8, v[8:9]
	v_lshl_add_u64 v[12:13], s[0:1], 0, v[8:9]
	ds_read_b128 v[8:11], v26
	v_lshlrev_b32_e32 v3, 5, v7
	v_and_b32_e32 v138, 0xe0, v3
	v_lshl_add_u64 v[24:25], v[12:13], 0, v[138:139]
	ds_read_b128 v[12:15], v26 offset:16896
	s_waitcnt lgkmcnt(1)
	v_lshlrev_b32_e32 v16, 16, v8
	v_and_b32_e32 v17, 0xffff0000, v8
	v_add_u32_e32 v8, 32, v2
	v_lshlrev_b32_e32 v18, 16, v9
	v_and_b32_e32 v19, 0xffff0000, v9
	v_ashrrev_i32_e32 v9, 31, v8
	v_lshl_add_u64 v[8:9], v[4:5], 0, v[8:9]
	v_lshlrev_b64 v[8:9], 8, v[8:9]
	v_lshlrev_b32_e32 v22, 16, v11
	v_lshlrev_b32_e32 v20, 16, v10
	v_and_b32_e32 v23, 0xffff0000, v11
	v_and_b32_e32 v21, 0xffff0000, v10
	v_lshl_add_u64 v[8:9], s[0:1], 0, v[8:9]
	s_waitcnt lgkmcnt(0)
	v_lshlrev_b32_e32 v10, 16, v13
	v_lshl_add_u64 v[20:21], v[8:9], 0, v[138:139]
	v_lshlrev_b32_e32 v8, 16, v12
	v_lshlrev_b32_e32 v18, 16, v15
	v_lshlrev_b32_e32 v16, 16, v14
	v_and_b32_e32 v19, 0xffff0000, v15
	v_and_b32_e32 v17, 0xffff0000, v14
	v_and_b32_e32 v11, 0xffff0000, v13
	v_and_b32_e32 v9, 0xffff0000, v12
	s_nop 1
	v_add_u32_e32 v8, 64, v2
	v_ashrrev_i32_e32 v9, 31, v8
	v_lshl_add_u64 v[12:13], v[4:5], 0, v[8:9]
	ds_read_b128 v[8:11], v26 offset:33792
	v_lshlrev_b64 v[12:13], 8, v[12:13]
	v_lshl_add_u64 v[12:13], s[0:1], 0, v[12:13]
	v_lshl_add_u64 v[24:25], v[12:13], 0, v[138:139]
	ds_read_b128 v[12:15], v26 offset:50688
	s_waitcnt lgkmcnt(1)
	v_lshlrev_b32_e32 v16, 16, v8
	v_and_b32_e32 v17, 0xffff0000, v8
	v_add_u32_e32 v8, 0x60, v2
	v_lshlrev_b32_e32 v18, 16, v9
	v_and_b32_e32 v19, 0xffff0000, v9
	v_ashrrev_i32_e32 v9, 31, v8
	v_lshl_add_u64 v[4:5], v[4:5], 0, v[8:9]
	v_lshlrev_b64 v[4:5], 8, v[4:5]
	v_lshlrev_b32_e32 v22, 16, v11
	v_lshlrev_b32_e32 v20, 16, v10
	v_and_b32_e32 v23, 0xffff0000, v11
	v_and_b32_e32 v21, 0xffff0000, v10
	v_lshl_add_u64 v[4:5], s[0:1], 0, v[4:5]
	v_lshl_add_u64 v[4:5], v[4:5], 0, v[138:139]
	s_waitcnt lgkmcnt(0)
	v_lshlrev_b32_e32 v10, 16, v13
	v_lshlrev_b32_e32 v18, 16, v15
	v_lshlrev_b32_e32 v16, 16, v14
	v_and_b32_e32 v19, 0xffff0000, v15
	v_and_b32_e32 v17, 0xffff0000, v14
	v_lshlrev_b32_e32 v8, 16, v12
	v_and_b32_e32 v11, 0xffff0000, v13
	v_and_b32_e32 v9, 0xffff0000, v12

.LBB0_1288:
	s_cmp_lt_i32 s40, 8
	s_cselect_b64 s[24:25], -1, 0
	s_and_b64 s[26:27], s[24:25], exec
	s_cselect_b32 s8, s33, 0x9280000
	v_lshl_add_u32 v8, v6, 4, s39
	v_mul_lo_u32 v9, v2, s31
	s_add_u32 s26, s10, s8
	v_add_u32_e32 v10, v8, v9
	s_addc_u32 s27, s11, 0
	v_lshlrev_b32_e32 v7, 3, v7
	s_add_i32 s8, s37, s43
	ds_read_b128 v[12:15], v10
	v_and_b32_e32 v11, 56, v7
	v_or_b32_e32 v6, s8, v3
	v_lshl_add_u64 v[4:5], v[4:5], 1, s[26:27]
	v_lshlrev_b32_e32 v138, 1, v11
	v_ashrrev_i32_e32 v7, 31, v6
	v_ashrrev_i32_e32 v3, 31, v2
	v_lshl_add_u64 v[4:5], v[4:5], 0, v[138:139]
	s_or_b64 s[6:7], s[6:7], s[24:25]
	v_lshlrev_b64 v[6:7], 8, v[6:7]
	v_lshlrev_b64 v[16:17], 7, v[2:3]
	s_mov_b64 s[24:25], -1
	v_or_b32_e32 v6, s38, v6
	v_lshl_add_u64 v[16:17], v[4:5], 0, v[16:17]
	s_and_b64 vcc, exec, s[6:7]
	v_lshlrev_b32_e32 v138, 2, v11
	s_waitcnt lgkmcnt(0)
	global_store_dwordx4 v[16:17], v[12:15], off
	s_cbranch_vccnz .LBB0_1290
	ds_read_b128 v[12:15], v10
	v_lshl_add_u64 v[16:17], v[6:7], 0, v[2:3]
	v_lshlrev_b64 v[16:17], 8, v[16:17]
	v_lshl_add_u64 v[16:17], s[4:5], 0, v[16:17]
	v_lshl_add_u64 v[28:29], v[16:17], 0, v[138:139]
	ds_read_b128 v[16:19], v10 offset:16896
	s_waitcnt lgkmcnt(1)
	v_lshlrev_b32_e32 v20, 16, v12
	v_and_b32_e32 v21, 0xffff0000, v12
	v_add_u32_e32 v12, 32, v2
	v_lshlrev_b32_e32 v22, 16, v13
	v_and_b32_e32 v23, 0xffff0000, v13
	v_ashrrev_i32_e32 v13, 31, v12
	v_lshlrev_b32_e32 v26, 16, v15
	v_lshlrev_b32_e32 v24, 16, v14
	v_and_b32_e32 v27, 0xffff0000, v15
	v_and_b32_e32 v25, 0xffff0000, v14
	v_lshlrev_b64 v[14:15], 7, v[12:13]
	v_lshl_add_u64 v[12:13], v[6:7], 0, v[12:13]
	v_lshlrev_b64 v[12:13], 8, v[12:13]
	v_lshl_add_u64 v[12:13], s[4:5], 0, v[12:13]
	v_lshl_add_u64 v[14:15], v[4:5], 0, v[14:15]
	v_lshl_add_u64 v[24:25], v[12:13], 0, v[138:139]
	s_waitcnt lgkmcnt(0)
	v_lshlrev_b32_e32 v22, 16, v19
	v_lshlrev_b32_e32 v20, 16, v18
	v_and_b32_e32 v23, 0xffff0000, v19
	v_and_b32_e32 v21, 0xffff0000, v18
	s_mov_b64 s[24:25], 0
	global_store_dwordx4 v[14:15], v[16:19], off
	v_lshlrev_b32_e32 v14, 16, v17
	v_lshlrev_b32_e32 v12, 16, v16
	v_and_b32_e32 v15, 0xffff0000, v17
	v_and_b32_e32 v13, 0xffff0000, v16

.LBB0_1292:
	v_add_u32_e32 v9, 0x8400, v9
	s_nop 0
	v_add_u32_e32 v10, v8, v9
	ds_read_b128 v[12:15], v10
	v_add_u32_e32 v8, 64, v2
	v_ashrrev_i32_e32 v9, 31, v8
	v_lshlrev_b64 v[16:17], 7, v[8:9]
	s_xor_b64 s[6:7], s[6:7], -1
	v_lshl_add_u64 v[16:17], v[4:5], 0, v[16:17]
	s_andn2_b64 vcc, exec, s[6:7]
	s_mov_b64 s[6:7], -1
	s_waitcnt lgkmcnt(0)
	global_store_dwordx4 v[16:17], v[12:15], off
	s_cbranch_vccnz .LBB0_1294
	ds_read_b128 v[12:15], v10
	ds_read_b128 v[16:19], v10 offset:16896
	v_lshl_add_u64 v[8:9], v[6:7], 0, v[8:9]
	v_lshlrev_b64 v[8:9], 8, v[8:9]
	v_lshl_add_u64 v[8:9], s[4:5], 0, v[8:9]
	v_lshl_add_u64 v[8:9], v[8:9], 0, v[138:139]
	s_waitcnt lgkmcnt(1)
	v_lshlrev_b32_e32 v26, 16, v15
	v_lshlrev_b32_e32 v24, 16, v14
	v_and_b32_e32 v27, 0xffff0000, v15
	v_and_b32_e32 v25, 0xffff0000, v14
	v_lshlrev_b32_e32 v22, 16, v13
	v_lshlrev_b32_e32 v20, 16, v12
	v_and_b32_e32 v23, 0xffff0000, v13
	v_and_b32_e32 v21, 0xffff0000, v12
	v_add_u32_e32 v8, 0x60, v2
	v_ashrrev_i32_e32 v9, 31, v8
	v_lshl_add_u64 v[6:7], v[6:7], 0, v[8:9]
	v_lshlrev_b64 v[12:13], 7, v[8:9]
	v_lshlrev_b64 v[6:7], 8, v[6:7]
	v_lshl_add_u64 v[12:13], v[4:5], 0, v[12:13]
	v_lshl_add_u64 v[6:7], s[4:5], 0, v[6:7]
	s_waitcnt lgkmcnt(0)
	global_store_dwordx4 v[12:13], v[16:19], off
	v_lshl_add_u64 v[20:21], v[6:7], 0, v[138:139]
	v_lshlrev_b32_e32 v14, 16, v19
	v_lshlrev_b32_e32 v12, 16, v18
	v_and_b32_e32 v15, 0xffff0000, v19
	v_and_b32_e32 v13, 0xffff0000, v18
	s_mov_b64 s[6:7], 0
	v_lshlrev_b32_e32 v8, 16, v17
	v_lshlrev_b32_e32 v6, 16, v16
	v_and_b32_e32 v9, 0xffff0000, v17
	v_and_b32_e32 v7, 0xffff0000, v16
